# finalize: per-head gain vector staged once per phase in LDS instead of 6 L2 loads per row; counted waits re-derived
# speedup vs baseline: 1.0021x; 1.0021x over previous
.LBB0_615:
	s_or_b64 exec, exec, s[4:5]
	v_mov_b32_e32 v1, v188
	v_mov_b32_e32 v2, 0x21d28
	s_waitcnt lgkmcnt(0)
	s_barrier
	v_readlane_b32 s4, v238, 8
	v_add_u32_e32 v2, 0, v2
	ds_read_b64 v[2:3], v2
	v_ashrrev_i32_e32 v0, 6, v1
	s_mul_i32 s48, s58, 0xc0
	s_waitcnt lgkmcnt(0)
	v_readfirstlane_b32 s1, v2
	v_mov_b32_e32 v2, 0x21d28
	v_readfirstlane_b32 s0, v3
	v_add_u32_e32 v2, 0, v2
	ds_read_b64 v[2:3], v2
	s_waitcnt lgkmcnt(0)
	v_readfirstlane_b32 s7, v2
	v_mov_b32_e32 v2, 0x21d28
	v_readfirstlane_b32 s6, v3
	v_add_u32_e32 v2, 0, v2
	ds_read_b64 v[2:3], v2
	s_waitcnt lgkmcnt(0)
	v_readfirstlane_b32 s10, v2
	v_mov_b32_e32 v2, 0x21d28
	v_readfirstlane_b32 s11, v3
	v_add_u32_e32 v2, 0, v2
	ds_read_b64 v[2:3], v2
	s_waitcnt lgkmcnt(0)
	v_readfirstlane_b32 s12, v2
	v_mov_b32_e32 v2, 0x21ce8
	v_readfirstlane_b32 s13, v3
	v_add_u32_e32 v2, 0, v2
	ds_read_b64 v[2:3], v2
	s_waitcnt lgkmcnt(0)
	v_readfirstlane_b32 s16, v2
	v_mov_b32_e32 v2, 0x21cf0
	v_readfirstlane_b32 s2, v3
	v_add_u32_e32 v2, 0, v2
	ds_read_b64 v[2:3], v2
	s_waitcnt lgkmcnt(0)
	v_readfirstlane_b32 s20, v2
	v_add_u32_e32 v2, s4, v0
	s_mov_b32 s4, 0x14800
	v_readfirstlane_b32 s17, v3
	v_cmp_gt_i32_e32 vcc, s4, v2
	s_and_saveexec_b64 s[4:5], vcc
	s_cbranch_execz .LBB0_632
	s_add_u32 s8, s7, 0x12878000
	v_bfe_u32 v36, v1, 3, 3
	s_addc_u32 s9, s6, 0
	v_and_b32_e32 v3, 7, v1
	v_mul_u32_u24_e32 v4, 0xc0, v36
	s_add_u32 s6, s1, 0xb078000
	v_lshlrev_b32_e32 v164, 1, v4
	v_lshlrev_b32_e32 v4, 4, v3
	v_mov_b32_e32 v5, v165
	s_addc_u32 s7, s0, 0
	v_lshlrev_b32_e32 v40, 3, v3
	v_lshl_add_u64 v[4:5], s[10:11], 0, v[4:5]
	s_mov_b64 s[0:1], 0x5b38000
	v_cmp_gt_u32_e32 vcc, 4, v3
	v_lshlrev_b32_e32 v3, 6, v1
	v_lshl_add_u64 v[42:43], v[4:5], 0, s[0:1]
	v_and_b32_e32 v4, 64, v3
	v_mov_b32_e32 v5, v165
	v_lshl_add_u64 v[4:5], s[12:13], 0, v[4:5]
	s_mov_b64 s[0:1], 0x1fa7c000
	v_lshl_add_u64 v[44:45], v[4:5], 0, s[0:1]
	v_mad_i64_i32 v[2:3], s[0:1], v2, s23, v[164:165]
	v_and_b32_e32 v1, 2, v1
	v_readlane_b32 s0, v238, 7
	v_lshl_add_u64 v[38:39], s[6:7], 0, v[164:165]
	v_cmp_eq_u32_e64 s[36:37], 0, v1
	v_lshl_add_u64 v[46:47], s[6:7], 0, v[2:3]
	v_add_u32_e32 v164, s0, v0
	s_mov_b64 s[10:11], 0
	v_lshlrev_b32_e32 v48, 2, v40
	s_lshl_b64 s[100:101], s[48:49], 2
	s_add_u32 s100, s100, s20
	s_addc_u32 s101, s101, s17
	v_lshlrev_b32_e32 v231, 4, v188
	v_min_u32_e32 v231, 0x2f0, v231
	global_load_dwordx4 v[232:235], v231, s[100:101]
	s_waitcnt vmcnt(0)
	ds_write_b128 v231, v[232:235]
	s_waitcnt lgkmcnt(0)
	s_barrier
	s_branch .LBB0_619

.LBB0_627:
	s_or_b64 exec, exec, s[12:13]
	s_mov_b32 s0, 0xa000
	v_mov_b32_e32 v16, s17
	v_mov_b32_e32 v17, s2
	v_cmp_gt_i32_e64 s[40:41], s0, v58
	v_mov_b32_e32 v18, s16
	s_waitcnt vmcnt(2)
	v_lshlrev_b32_e32 v59, 16, v12
	v_cndmask_b32_e64 v17, v16, v17, s[40:41]
	v_mov_b32_e32 v16, s20
	v_cndmask_b32_e64 v16, v16, v18, s[40:41]
	v_and_b32_e32 v55, 0xffff0000, v12
	v_lshlrev_b32_e32 v53, 16, v13
	v_and_b32_e32 v41, 0xffff0000, v13
	v_lshl_add_u64 v[12:13], s[48:49], 2, v[16:17]
	v_mov_b32_e32 v49, v165
	v_lshl_add_u64 v[16:17], v[12:13], 0, v[48:49]
	ds_read_b128 v[72:75], v48 offset:528
	ds_read_b128 v[76:79], v48 offset:512
	v_lshlrev_b32_e32 v37, 16, v14
	v_and_b32_e32 v70, 0xffff0000, v14
	v_lshlrev_b32_e32 v69, 16, v15
	v_and_b32_e32 v66, 0xffff0000, v15
	ds_read_b128 v[20:23], v48 offset:16
	ds_read_b128 v[24:27], v48
	ds_read_b128 v[12:15], v48 offset:272
	s_nop 0
	ds_read_b128 v[16:19], v48 offset:256
	v_mul_f32_e32 v71, v55, v55
	v_fmac_f32_e32 v71, v59, v59
	v_fmac_f32_e32 v71, v53, v53
	v_fmac_f32_e32 v71, v41, v41
	v_fmac_f32_e32 v71, v37, v37
	v_fmac_f32_e32 v71, v70, v70
	v_fmac_f32_e32 v71, v69, v69
	s_waitcnt vmcnt(1)
	v_lshlrev_b32_e32 v64, 16, v32
	v_fmac_f32_e32 v71, v66, v66
	v_and_b32_e32 v62, 0xffff0000, v32
	v_fmac_f32_e32 v71, v64, v64
	v_lshlrev_b32_e32 v60, 16, v33
	v_fmac_f32_e32 v71, v62, v62
	v_and_b32_e32 v67, 0xffff0000, v33
	v_fmac_f32_e32 v71, v60, v60
	v_lshlrev_b32_e32 v65, 16, v34
	v_fmac_f32_e32 v71, v67, v67
	v_and_b32_e32 v63, 0xffff0000, v34
	v_fmac_f32_e32 v71, v65, v65
	v_lshlrev_b32_e32 v61, 16, v35
	v_fmac_f32_e32 v71, v63, v63
	v_and_b32_e32 v49, 0xffff0000, v35
	s_waitcnt vmcnt(0)
	v_lshlrev_b32_e32 v32, 16, v28
	v_and_b32_e32 v33, 0xffff0000, v28
	v_fmac_f32_e32 v71, v61, v61
	v_fmac_f32_e32 v71, v49, v49
	v_pk_mul_f32 v[86:87], v[32:33], v[32:33]
	v_lshlrev_b32_e32 v28, 16, v29
	v_and_b32_e32 v29, 0xffff0000, v29
	v_add_f32_e32 v71, v86, v71
	v_pk_mul_f32 v[84:85], v[28:29], v[28:29]
	v_add_f32_e32 v71, v87, v71
	v_lshlrev_b32_e32 v80, 16, v30
	v_and_b32_e32 v81, 0xffff0000, v30
	v_add_f32_e32 v71, v84, v71
	v_pk_mul_f32 v[34:35], v[80:81], v[80:81]
	v_add_f32_e32 v71, v85, v71
	v_lshlrev_b32_e32 v82, 16, v31
	v_and_b32_e32 v83, 0xffff0000, v31
	v_add_f32_e32 v34, v34, v71
	v_pk_mul_f32 v[30:31], v[82:83], v[82:83]
	v_add_f32_e32 v34, v35, v34
	v_add_f32_e32 v30, v30, v34
	v_add_f32_e32 v30, v31, v30
	ds_swizzle_b32 v31, v30 offset:swizzle(SWAP,1)
	v_cndmask_b32_e64 v71, v164, v58, s[40:41]
	s_waitcnt lgkmcnt(0)
	v_add_f32_e32 v30, v30, v31
	ds_swizzle_b32 v31, v30 offset:swizzle(SWAP,2)
	s_waitcnt lgkmcnt(0)
	v_add_f32_e32 v30, v30, v31
	ds_swizzle_b32 v31, v30 offset:swizzle(SWAP,4)
	s_waitcnt lgkmcnt(0)
	v_add_f32_e32 v30, v30, v31
	v_fmamk_f32 v30, v30, 0x3baaaaab, v189
	v_mul_f32_e32 v31, 0x4b800000, v30
	v_cmp_gt_f32_e64 s[42:43], s28, v30
	s_nop 1
	v_cndmask_b32_e64 v30, v30, v31, s[42:43]
	v_rsq_f32_e32 v30, v30
	s_nop 0
	v_mul_f32_e32 v31, 0x45800000, v30
	v_cndmask_b32_e64 v58, v30, v31, s[42:43]
	s_waitcnt vmcnt(0) lgkmcnt(0)
	v_pk_mul_f32 v[30:31], v[58:59], v[76:77] op_sel_hi:[0,1]
	v_pk_mul_f32 v[76:77], v[58:59], v[78:79] op_sel_hi:[0,1]
	v_pk_mul_f32 v[34:35], v[30:31], v[32:33]
	v_pk_mul_f32 v[32:33], v[76:77], v[28:29]
	v_pk_mul_f32 v[28:29], v[58:59], v[72:73] op_sel_hi:[0,1]
	v_pk_mul_f32 v[30:31], v[28:29], v[80:81]
	v_pk_mul_f32 v[28:29], v[58:59], v[74:75] op_sel_hi:[0,1]
	v_add_u32_e32 v72, 0xffffe000, v71
	v_pk_mul_f32 v[28:29], v[28:29], v[82:83]
	v_cmp_gt_u32_e64 s[42:43], s89, v72
	s_and_saveexec_b64 s[12:13], s[42:43]
	s_cbranch_execz .LBB0_629
	v_lshrrev_b32_e32 v72, 6, v71
	v_cndmask_b32_e32 v71, v71, v72, vcc
	v_lshlrev_b32_e32 v71, 7, v71
	v_and_b32_e32 v72, 0x1f80, v71
	v_mov_b32_e32 v73, v165
	v_lshl_add_u64 v[84:85], v[44:45], 0, v[72:73]
	global_load_dwordx4 v[72:75], v[84:85], off offset:48
	global_load_dwordx4 v[76:79], v[84:85], off offset:32
	global_load_dwordx4 v[80:83], v[84:85], off offset:16
	s_nop 0
	global_load_dwordx4 v[84:87], v[84:85], off
	ds_swizzle_b32 v88, v34 offset:swizzle(SWAP,2)
	ds_swizzle_b32 v89, v35 offset:swizzle(SWAP,2)
	s_waitcnt vmcnt(0)
	v_mov_b32_e32 v91, v86
	v_mov_b32_e32 v86, v85
	v_mov_b32_e32 v90, v84
	s_waitcnt lgkmcnt(0)
	v_pk_mul_f32 v[84:85], v[86:87], v[88:89]
	v_mov_b32_e32 v87, v82
	v_cndmask_b32_e64 v85, v85, -v85, s[36:37]
	v_cndmask_b32_e64 v84, v84, -v84, s[36:37]
	v_pk_fma_f32 v[34:35], v[34:35], v[90:91], v[84:85]
	ds_swizzle_b32 v84, v32 offset:swizzle(SWAP,2)
	ds_swizzle_b32 v85, v33 offset:swizzle(SWAP,2)
	v_mov_b32_e32 v82, v81
	v_mov_b32_e32 v86, v80
	s_waitcnt lgkmcnt(0)
	v_pk_mul_f32 v[80:81], v[82:83], v[84:85]
	s_nop 0
	v_cndmask_b32_e64 v81, v81, -v81, s[36:37]
	v_cndmask_b32_e64 v80, v80, -v80, s[36:37]
	v_pk_fma_f32 v[32:33], v[32:33], v[86:87], v[80:81]
	ds_swizzle_b32 v80, v30 offset:swizzle(SWAP,2)
	ds_swizzle_b32 v81, v31 offset:swizzle(SWAP,2)
	v_mov_b32_e32 v83, v78
	v_mov_b32_e32 v78, v77
	v_mov_b32_e32 v82, v76
	s_waitcnt lgkmcnt(0)
	v_pk_mul_f32 v[76:77], v[78:79], v[80:81]
	s_nop 0
	v_cndmask_b32_e64 v77, v77, -v77, s[36:37]
	v_cndmask_b32_e64 v76, v76, -v76, s[36:37]
	v_pk_fma_f32 v[30:31], v[30:31], v[82:83], v[76:77]
	ds_swizzle_b32 v76, v28 offset:swizzle(SWAP,2)
	ds_swizzle_b32 v77, v29 offset:swizzle(SWAP,2)
	v_mov_b32_e32 v79, v74
	v_mov_b32_e32 v74, v73
	v_mov_b32_e32 v78, v72
	s_waitcnt lgkmcnt(0)
	v_pk_mul_f32 v[72:73], v[74:75], v[76:77]
	s_nop 0
	v_cndmask_b32_e64 v73, v73, -v73, s[36:37]
	v_cndmask_b32_e64 v72, v72, -v72, s[36:37]
	v_pk_fma_f32 v[28:29], v[28:29], v[78:79], v[72:73]
.LBB0_629:
	s_or_b64 exec, exec, s[12:13]
	s_waitcnt vmcnt(0)
	v_mul_f32_e32 v20, v20, v58
	s_waitcnt vmcnt(0)
	v_mul_f32_e32 v12, v58, v12
	v_mul_f32_e32 v27, v27, v58
	v_mul_f32_e32 v20, v20, v37
	v_mul_f32_e32 v37, v12, v65
	v_mul_f32_e32 v12, v58, v13
	v_mul_f32_e32 v24, v24, v58
	v_mul_f32_e32 v25, v25, v58
	v_mul_f32_e32 v26, v26, v58
	v_mul_f32_e32 v27, v27, v41
	v_mul_f32_e32 v41, v12, v63
	v_mul_f32_e32 v12, v58, v14
	v_mul_f32_e32 v24, v24, v59
	v_mul_f32_e32 v25, v25, v55
	v_mul_f32_e32 v26, v26, v53
	v_mul_f32_e32 v53, v12, v61
	v_mul_f32_e32 v12, v58, v15
	v_cndmask_b32_e64 v55, 1.0, v194, s[40:41]
	v_mul_f32_e32 v21, v21, v58
	v_mul_f32_e32 v49, v12, v49
	v_mul_f32_e32 v12, v55, v24
	v_mul_f32_e32 v13, v55, v25
	v_mul_f32_e32 v21, v21, v70
	v_mul_f32_e32 v22, v22, v58
	v_cvt_pk_bf16_f32 v12, v12, v13
	v_mul_f32_e32 v13, v55, v26
	v_mul_f32_e32 v14, v55, v27
	v_mul_f32_e32 v22, v22, v69
	v_mul_f32_e32 v23, v23, v58
	s_waitcnt vmcnt(0)
	v_mul_f32_e32 v16, v58, v16
	v_mul_f32_e32 v17, v58, v17
	v_cvt_pk_bf16_f32 v13, v13, v14
	v_mul_f32_e32 v14, v55, v20
	v_mul_f32_e32 v15, v55, v21
	v_mul_f32_e32 v23, v23, v66
	v_mul_f32_e32 v16, v16, v64
	v_mul_f32_e32 v17, v17, v62
	v_mul_f32_e32 v18, v58, v18
	v_mul_f32_e32 v19, v58, v19
	v_cvt_pk_bf16_f32 v14, v14, v15
	v_mul_f32_e32 v15, v55, v22
	v_mul_f32_e32 v18, v18, v60
	v_mul_f32_e32 v19, v19, v67
	v_mul_f32_e32 v20, v55, v23
	v_cvt_pk_bf16_f32 v15, v15, v20
	global_store_dwordx4 v[56:57], v[12:15], off
	s_nop 1
	v_mul_f32_e32 v12, v55, v16
	v_mul_f32_e32 v13, v55, v17
	v_cvt_pk_bf16_f32 v12, v12, v13
	v_mul_f32_e32 v13, v55, v18
	v_mul_f32_e32 v14, v55, v19
	v_cvt_pk_bf16_f32 v13, v13, v14
	v_mul_f32_e32 v14, v55, v37
	v_mul_f32_e32 v15, v55, v41
	v_cvt_pk_bf16_f32 v14, v14, v15
	v_mul_f32_e32 v15, v55, v53
	v_mul_f32_e32 v16, v55, v49
	v_cvt_pk_bf16_f32 v15, v15, v16
	global_store_dwordx4 v[56:57], v[12:15], off offset:128
	v_mul_f32_e32 v16, v55, v29
	s_nop 0
	v_mul_f32_e32 v12, v55, v34
	v_mul_f32_e32 v13, v55, v35
	v_cvt_pk_bf16_f32 v12, v12, v13
	v_mul_f32_e32 v13, v55, v32
	v_mul_f32_e32 v14, v55, v33
	v_cvt_pk_bf16_f32 v13, v13, v14
	v_mul_f32_e32 v14, v55, v30
	v_mul_f32_e32 v15, v55, v31
	v_cvt_pk_bf16_f32 v14, v14, v15
	v_mul_f32_e32 v15, v55, v28
	v_cvt_pk_bf16_f32 v15, v15, v16
	global_store_dwordx4 v[56:57], v[12:15], off offset:256
	s_and_saveexec_b64 s[12:13], s[38:39]
	s_cbranch_execz .LBB0_618
	v_cmp_gt_i32_e64 s[38:39], s0, v68
	v_mov_b32_e32 v12, s17
	v_mov_b32_e32 v13, s2
	v_cndmask_b32_e64 v13, v12, v13, s[38:39]
	v_mov_b32_e32 v12, s20
	v_mov_b32_e32 v14, s16
	v_cndmask_b32_e64 v12, v12, v14, s[38:39]
	v_lshl_add_u64 v[12:13], s[48:49], 2, v[12:13]
	v_mov_b32_e32 v49, v165
	v_lshl_add_u64 v[74:75], v[12:13], 0, v[48:49]
	ds_read_b128 v[20:23], v48 offset:16
	ds_read_b128 v[24:27], v48
	ds_read_b128 v[12:15], v48 offset:272
	ds_read_b128 v[16:19], v48 offset:256
	ds_read_b128 v[70:73], v48 offset:528
	s_nop 0
	ds_read_b128 v[74:77], v48 offset:512
	v_and_b32_e32 v66, 0xffff0000, v0
	v_lshlrev_b32_e32 v67, 16, v0
	v_cndmask_b32_e64 v68, v54, v68, s[38:39]
	v_mul_f32_e32 v54, v66, v66
	v_lshlrev_b32_e32 v65, 16, v1
	v_fmac_f32_e32 v54, v67, v67
	v_and_b32_e32 v64, 0xffff0000, v1
	v_fmac_f32_e32 v54, v65, v65
	v_lshlrev_b32_e32 v63, 16, v2
	v_fmac_f32_e32 v54, v64, v64
	v_and_b32_e32 v62, 0xffff0000, v2
	v_fmac_f32_e32 v54, v63, v63
	v_lshlrev_b32_e32 v61, 16, v3
	v_fmac_f32_e32 v54, v62, v62
	v_and_b32_e32 v60, 0xffff0000, v3
	v_fmac_f32_e32 v54, v61, v61
	v_lshlrev_b32_e32 v59, 16, v4
	v_fmac_f32_e32 v54, v60, v60
	v_and_b32_e32 v58, 0xffff0000, v4
	v_fmac_f32_e32 v54, v59, v59
	v_lshlrev_b32_e32 v57, 16, v5
	v_fmac_f32_e32 v54, v58, v58
	v_and_b32_e32 v56, 0xffff0000, v5
	v_fmac_f32_e32 v54, v57, v57
	v_lshlrev_b32_e32 v55, 16, v6
	v_fmac_f32_e32 v54, v56, v56
	v_and_b32_e32 v53, 0xffff0000, v6
	v_fmac_f32_e32 v54, v55, v55
	v_lshlrev_b32_e32 v41, 16, v7
	v_fmac_f32_e32 v54, v53, v53
	v_and_b32_e32 v37, 0xffff0000, v7
	v_and_b32_e32 v35, 0xffff0000, v8
	v_lshlrev_b32_e32 v34, 16, v8
	v_fmac_f32_e32 v54, v41, v41
	v_fmac_f32_e32 v54, v37, v37
	v_pk_mul_f32 v[84:85], v[34:35], v[34:35]
	v_and_b32_e32 v33, 0xffff0000, v9
	v_lshlrev_b32_e32 v32, 16, v9
	v_add_f32_e32 v49, v84, v54
	v_pk_mul_f32 v[82:83], v[32:33], v[32:33]
	v_add_f32_e32 v49, v85, v49
	v_and_b32_e32 v31, 0xffff0000, v10
	v_lshlrev_b32_e32 v30, 16, v10
	v_add_f32_e32 v49, v82, v49
	v_pk_mul_f32 v[80:81], v[30:31], v[30:31]
	v_add_f32_e32 v49, v83, v49
	v_and_b32_e32 v29, 0xffff0000, v11
	v_lshlrev_b32_e32 v28, 16, v11
	v_add_f32_e32 v49, v80, v49
	v_pk_mul_f32 v[78:79], v[28:29], v[28:29]
	v_add_f32_e32 v49, v81, v49
	v_add_f32_e32 v49, v78, v49
	v_add_f32_e32 v49, v79, v49
	ds_swizzle_b32 v54, v49 offset:swizzle(SWAP,1)
	s_waitcnt lgkmcnt(0)
	v_add_f32_e32 v49, v49, v54
	ds_swizzle_b32 v54, v49 offset:swizzle(SWAP,2)
	s_waitcnt lgkmcnt(0)
	v_add_f32_e32 v49, v49, v54
	ds_swizzle_b32 v54, v49 offset:swizzle(SWAP,4)
	s_waitcnt lgkmcnt(0)
	v_add_f32_e32 v49, v49, v54
	v_fmamk_f32 v49, v49, 0x3baaaaab, v189
	v_cmp_gt_f32_e64 s[40:41], s28, v49
	v_mul_f32_e32 v54, 0x4b800000, v49
	s_nop 0
	v_cndmask_b32_e64 v49, v49, v54, s[40:41]
	v_rsq_f32_e32 v49, v49
	s_nop 0
	v_mul_f32_e32 v54, 0x45800000, v49
	v_cndmask_b32_e64 v54, v49, v54, s[40:41]
	s_waitcnt vmcnt(0) lgkmcnt(0)
	v_pk_mul_f32 v[74:75], v[54:55], v[74:75] op_sel_hi:[0,1]
	v_pk_mul_f32 v[70:71], v[54:55], v[70:71] op_sel_hi:[0,1]
	v_pk_mul_f32 v[34:35], v[74:75], v[34:35]
	v_pk_mul_f32 v[74:75], v[54:55], v[76:77] op_sel_hi:[0,1]
	v_pk_mul_f32 v[30:31], v[70:71], v[30:31]
	v_pk_mul_f32 v[70:71], v[54:55], v[72:73] op_sel_hi:[0,1]
	v_add_u32_e32 v49, 0xffffe000, v68
	v_pk_mul_f32 v[32:33], v[74:75], v[32:33]
	v_pk_mul_f32 v[28:29], v[70:71], v[28:29]
	v_cmp_gt_u32_e64 s[40:41], s89, v49
	s_and_saveexec_b64 s[14:15], s[40:41]
	s_cbranch_execz .LBB0_617
	v_lshrrev_b32_e32 v49, 6, v68
	v_cndmask_b32_e32 v49, v68, v49, vcc
	v_lshlrev_b32_e32 v49, 7, v49
	v_and_b32_e32 v68, 0x1f80, v49
	v_mov_b32_e32 v69, v165
	v_lshl_add_u64 v[80:81], v[44:45], 0, v[68:69]
	global_load_dwordx4 v[68:71], v[80:81], off offset:48
	global_load_dwordx4 v[72:75], v[80:81], off offset:32
	global_load_dwordx4 v[76:79], v[80:81], off offset:16
	s_nop 0
	global_load_dwordx4 v[80:83], v[80:81], off
	ds_swizzle_b32 v84, v34 offset:swizzle(SWAP,2)
	ds_swizzle_b32 v85, v35 offset:swizzle(SWAP,2)
	s_waitcnt vmcnt(0)
	v_mov_b32_e32 v87, v82
	v_mov_b32_e32 v82, v81
	v_mov_b32_e32 v86, v80
	s_waitcnt lgkmcnt(0)
	v_pk_mul_f32 v[80:81], v[82:83], v[84:85]
	v_mov_b32_e32 v83, v78
	v_cndmask_b32_e64 v81, v81, -v81, s[36:37]
	v_cndmask_b32_e64 v80, v80, -v80, s[36:37]
	v_pk_fma_f32 v[34:35], v[34:35], v[86:87], v[80:81]
	ds_swizzle_b32 v80, v32 offset:swizzle(SWAP,2)
	ds_swizzle_b32 v81, v33 offset:swizzle(SWAP,2)
	v_mov_b32_e32 v78, v77
	v_mov_b32_e32 v82, v76
	s_waitcnt lgkmcnt(0)
	v_pk_mul_f32 v[76:77], v[78:79], v[80:81]
	s_nop 0
	v_cndmask_b32_e64 v77, v77, -v77, s[36:37]
	v_cndmask_b32_e64 v76, v76, -v76, s[36:37]
	v_pk_fma_f32 v[32:33], v[32:33], v[82:83], v[76:77]
	ds_swizzle_b32 v76, v30 offset:swizzle(SWAP,2)
	ds_swizzle_b32 v77, v31 offset:swizzle(SWAP,2)
	v_mov_b32_e32 v79, v74
	v_mov_b32_e32 v74, v73
	v_mov_b32_e32 v78, v72
	s_waitcnt lgkmcnt(0)
	v_pk_mul_f32 v[72:73], v[74:75], v[76:77]
	s_nop 0
	v_cndmask_b32_e64 v73, v73, -v73, s[36:37]
	v_cndmask_b32_e64 v72, v72, -v72, s[36:37]
	v_pk_fma_f32 v[30:31], v[30:31], v[78:79], v[72:73]
	ds_swizzle_b32 v72, v28 offset:swizzle(SWAP,2)
	ds_swizzle_b32 v73, v29 offset:swizzle(SWAP,2)
	v_mov_b32_e32 v75, v70
	v_mov_b32_e32 v70, v69
	v_mov_b32_e32 v74, v68
	s_waitcnt lgkmcnt(0)
	v_pk_mul_f32 v[68:69], v[70:71], v[72:73]
	s_nop 0
	v_cndmask_b32_e64 v69, v69, -v69, s[36:37]
	v_cndmask_b32_e64 v68, v68, -v68, s[36:37]
	v_pk_fma_f32 v[28:29], v[28:29], v[74:75], v[68:69]
	s_branch .LBB0_617
